# up-projection GEMM epilogue: packed rows lane-transposed with ds_bpermute so consecutive lanes store consecutive 16-byte pieces (coalesced 64-byte segments)
# speedup vs baseline: 1.0209x; 1.0109x over previous
.LBB0_1030:
	v_mbcnt_lo_u32_b32 v140, -1, 0
	v_mbcnt_hi_u32_b32 v140, -1, v140
	v_and_b32_e32 v141, 3, v140
	v_lshrrev_b32_e32 v148, 2, v140
	v_lshl_add_u32 v143, v141, 4, v148
	v_lshlrev_b32_e32 v143, 2, v143
	v_readfirstlane_b32 s24, v146
	s_lshl_b32 s11, s14, 8
	s_add_i32 s11, s11, s55
	s_lshl_b32 s13, s18, 8
	s_or_b32 s13, s13, s24
	v_add_u32_e32 v148, s11, v148
	v_lshl_add_u32 v141, v141, 3, s13
	v_lshlrev_b32_e32 v141, 1, v141
	v_mul_u32_u24_e32 v142, 0x2c00, v148
	v_add_u32_e32 v142, v142, v141
	s_ashr_i32 s26, s11, 4
	v_cvt_pk_bf16_f32 v126, v126, v127
	v_cvt_pk_bf16_f32 v127, v128, v129
	v_cvt_pk_bf16_f32 v128, v122, v123
	v_cvt_pk_bf16_f32 v129, v124, v125
	ds_bpermute_b32 v152, v143, v126
	ds_bpermute_b32 v153, v143, v127
	ds_bpermute_b32 v154, v143, v128
	ds_bpermute_b32 v155, v143, v129
	v_cvt_pk_bf16_f32 v118, v118, v119
	v_cvt_pk_bf16_f32 v119, v120, v121
	v_cvt_pk_bf16_f32 v120, v110, v111
	v_cvt_pk_bf16_f32 v121, v112, v113
	ds_bpermute_b32 v156, v143, v118
	ds_bpermute_b32 v157, v143, v119
	ds_bpermute_b32 v158, v143, v120
	ds_bpermute_b32 v159, v143, v121
	v_cvt_pk_bf16_f32 v114, v114, v115
	v_cvt_pk_bf16_f32 v115, v116, v117
	v_cvt_pk_bf16_f32 v116, v106, v107
	v_cvt_pk_bf16_f32 v117, v108, v109
	ds_bpermute_b32 v160, v143, v114
	ds_bpermute_b32 v161, v143, v115
	ds_bpermute_b32 v162, v143, v116
	ds_bpermute_b32 v163, v143, v117
	s_waitcnt lgkmcnt(8)
	s_add_u32 s24, s4, 0x0
	s_addc_u32 s25, s5, 0
	s_add_i32 s18, s26, 0
	s_mul_hi_u32 s15, s18, 0x2c00
	s_mul_i32 s14, s18, 0x2c00
	s_add_u32 s14, s6, s14
	s_addc_u32 s15, s7, s15
	global_store_dwordx4 v142, v[152:155], s[24:25]
	s_mov_b64 exec, 15
	global_store_dwordx4 v141, v[152:155], s[14:15]
	s_mov_b64 exec, -1
	v_cvt_pk_bf16_f32 v102, v102, v103
	v_cvt_pk_bf16_f32 v103, v104, v105
	v_cvt_pk_bf16_f32 v104, v94, v95
	v_cvt_pk_bf16_f32 v105, v96, v97
	ds_bpermute_b32 v164, v143, v102
	ds_bpermute_b32 v165, v143, v103
	ds_bpermute_b32 v166, v143, v104
	ds_bpermute_b32 v167, v143, v105
	s_waitcnt lgkmcnt(8)
	global_store_dwordx4 v142, v[156:159], s[24:25] offset:256
	s_mov_b64 exec, 15
	global_store_dwordx4 v141, v[156:159], s[14:15] offset:256
	s_mov_b64 exec, -1
	v_cvt_pk_bf16_f32 v98, v98, v99
	v_cvt_pk_bf16_f32 v99, v100, v101
	v_cvt_pk_bf16_f32 v100, v90, v91
	v_cvt_pk_bf16_f32 v101, v92, v93
	ds_bpermute_b32 v168, v143, v98
	ds_bpermute_b32 v169, v143, v99
	ds_bpermute_b32 v170, v143, v100
	ds_bpermute_b32 v171, v143, v101
	s_waitcnt lgkmcnt(8)
	s_add_u32 s24, s4, 0x2c000
	s_addc_u32 s25, s5, 0
	s_add_i32 s18, s26, 1
	s_mul_hi_u32 s15, s18, 0x2c00
	s_mul_i32 s14, s18, 0x2c00
	s_add_u32 s14, s6, s14
	s_addc_u32 s15, s7, s15
	global_store_dwordx4 v142, v[160:163], s[24:25]
	s_mov_b32 exec_lo, 0
	s_mov_b32 exec_hi, 0xf0000000
	global_store_dwordx4 v141, v[160:163], s[14:15]
	s_mov_b64 exec, -1
	v_cvt_pk_bf16_f32 v86, v86, v87
	v_cvt_pk_bf16_f32 v87, v88, v89
	v_cvt_pk_bf16_f32 v88, v78, v79
	v_cvt_pk_bf16_f32 v89, v80, v81
	ds_bpermute_b32 v172, v143, v86
	ds_bpermute_b32 v173, v143, v87
	ds_bpermute_b32 v174, v143, v88
	ds_bpermute_b32 v175, v143, v89
	s_waitcnt lgkmcnt(8)
	global_store_dwordx4 v142, v[164:167], s[24:25] offset:256
	s_mov_b32 exec_lo, 0
	s_mov_b32 exec_hi, 0xf0000000
	global_store_dwordx4 v141, v[164:167], s[14:15] offset:256
	s_mov_b64 exec, -1
	v_cvt_pk_bf16_f32 v82, v82, v83
	v_cvt_pk_bf16_f32 v83, v84, v85
	v_cvt_pk_bf16_f32 v84, v74, v75
	v_cvt_pk_bf16_f32 v85, v76, v77
	ds_bpermute_b32 v176, v143, v82
	ds_bpermute_b32 v177, v143, v83
	ds_bpermute_b32 v178, v143, v84
	ds_bpermute_b32 v179, v143, v85
	s_waitcnt lgkmcnt(8)
	s_add_u32 s24, s4, 0x58000
	s_addc_u32 s25, s5, 0
	s_add_i32 s18, s26, 2
	s_mul_hi_u32 s15, s18, 0x2c00
	s_mul_i32 s14, s18, 0x2c00
	s_add_u32 s14, s6, s14
	s_addc_u32 s15, s7, s15
	global_store_dwordx4 v142, v[168:171], s[24:25]
	s_mov_b64 exec, 15
	global_store_dwordx4 v141, v[168:171], s[14:15]
	s_mov_b64 exec, -1
	v_cvt_pk_bf16_f32 v70, v70, v71
	v_cvt_pk_bf16_f32 v71, v72, v73
	v_cvt_pk_bf16_f32 v72, v66, v67
	v_cvt_pk_bf16_f32 v73, v68, v69
	ds_bpermute_b32 v186, v143, v70
	ds_bpermute_b32 v187, v143, v71
	ds_bpermute_b32 v188, v143, v72
	ds_bpermute_b32 v189, v143, v73
	s_waitcnt lgkmcnt(8)
	global_store_dwordx4 v142, v[172:175], s[24:25] offset:256
	s_mov_b64 exec, 15
	global_store_dwordx4 v141, v[172:175], s[14:15] offset:256
	s_mov_b64 exec, -1
	v_cvt_pk_bf16_f32 v62, v62, v63
	v_cvt_pk_bf16_f32 v63, v64, v65
	v_cvt_pk_bf16_f32 v64, v58, v59
	v_cvt_pk_bf16_f32 v65, v60, v61
	ds_bpermute_b32 v190, v143, v62
	ds_bpermute_b32 v191, v143, v63
	ds_bpermute_b32 v192, v143, v64
	ds_bpermute_b32 v193, v143, v65
	s_waitcnt lgkmcnt(8)
	s_add_u32 s24, s4, 0x84000
	s_addc_u32 s25, s5, 0
	s_add_i32 s18, s26, 3
	s_mul_hi_u32 s15, s18, 0x2c00
	s_mul_i32 s14, s18, 0x2c00
	s_add_u32 s14, s6, s14
	s_addc_u32 s15, s7, s15
	global_store_dwordx4 v142, v[176:179], s[24:25]
	s_mov_b32 exec_lo, 0
	s_mov_b32 exec_hi, 0xf0000000
	global_store_dwordx4 v141, v[176:179], s[14:15]
	s_mov_b64 exec, -1
	v_cvt_pk_bf16_f32 v54, v54, v55
	v_cvt_pk_bf16_f32 v55, v56, v57
	v_cvt_pk_bf16_f32 v56, v46, v47
	v_cvt_pk_bf16_f32 v57, v48, v49
	ds_bpermute_b32 v212, v143, v54
	ds_bpermute_b32 v213, v143, v55
	ds_bpermute_b32 v214, v143, v56
	ds_bpermute_b32 v215, v143, v57
	s_waitcnt lgkmcnt(8)
	global_store_dwordx4 v142, v[186:189], s[24:25] offset:256
	s_mov_b32 exec_lo, 0
	s_mov_b32 exec_hi, 0xf0000000
	global_store_dwordx4 v141, v[186:189], s[14:15] offset:256
	s_mov_b64 exec, -1
	v_cvt_pk_bf16_f32 v50, v50, v51
	v_cvt_pk_bf16_f32 v51, v52, v53
	v_cvt_pk_bf16_f32 v52, v42, v43
	v_cvt_pk_bf16_f32 v53, v44, v45
	ds_bpermute_b32 v216, v143, v50
	ds_bpermute_b32 v217, v143, v51
	ds_bpermute_b32 v218, v143, v52
	ds_bpermute_b32 v219, v143, v53
	s_waitcnt lgkmcnt(8)
	s_add_u32 s24, s4, 0x160000
	s_addc_u32 s25, s5, 0
	s_add_i32 s18, s26, 8
	s_mul_hi_u32 s15, s18, 0x2c00
	s_mul_i32 s14, s18, 0x2c00
	s_add_u32 s14, s6, s14
	s_addc_u32 s15, s7, s15
	global_store_dwordx4 v142, v[190:193], s[24:25]
	s_mov_b64 exec, 15
	global_store_dwordx4 v141, v[190:193], s[14:15]
	s_mov_b64 exec, -1
	v_cvt_pk_bf16_f32 v38, v38, v39
	v_cvt_pk_bf16_f32 v39, v40, v41
	v_cvt_pk_bf16_f32 v40, v30, v31
	v_cvt_pk_bf16_f32 v41, v32, v33
	ds_bpermute_b32 v220, v143, v38
	ds_bpermute_b32 v221, v143, v39
	ds_bpermute_b32 v222, v143, v40
	ds_bpermute_b32 v223, v143, v41
	s_waitcnt lgkmcnt(8)
	global_store_dwordx4 v142, v[212:215], s[24:25] offset:256
	s_mov_b64 exec, 15
	global_store_dwordx4 v141, v[212:215], s[14:15] offset:256
	s_mov_b64 exec, -1
	v_cvt_pk_bf16_f32 v34, v34, v35
	v_cvt_pk_bf16_f32 v35, v36, v37
	v_cvt_pk_bf16_f32 v36, v26, v27
	v_cvt_pk_bf16_f32 v37, v28, v29
	ds_bpermute_b32 v224, v143, v34
	ds_bpermute_b32 v225, v143, v35
	ds_bpermute_b32 v226, v143, v36
	ds_bpermute_b32 v227, v143, v37
	s_waitcnt lgkmcnt(8)
	s_add_u32 s24, s4, 0x18c000
	s_addc_u32 s25, s5, 0
	s_add_i32 s18, s26, 9
	s_mul_hi_u32 s15, s18, 0x2c00
	s_mul_i32 s14, s18, 0x2c00
	s_add_u32 s14, s6, s14
	s_addc_u32 s15, s7, s15
	global_store_dwordx4 v142, v[216:219], s[24:25]
	s_mov_b32 exec_lo, 0
	s_mov_b32 exec_hi, 0xf0000000
	global_store_dwordx4 v141, v[216:219], s[14:15]
	s_mov_b64 exec, -1
	v_cvt_pk_bf16_f32 v22, v22, v23
	v_cvt_pk_bf16_f32 v23, v24, v25
	v_cvt_pk_bf16_f32 v24, v14, v15
	v_cvt_pk_bf16_f32 v25, v16, v17
	ds_bpermute_b32 v228, v143, v22
	ds_bpermute_b32 v229, v143, v23
	ds_bpermute_b32 v230, v143, v24
	ds_bpermute_b32 v231, v143, v25
	s_waitcnt lgkmcnt(8)
	global_store_dwordx4 v142, v[220:223], s[24:25] offset:256
	s_mov_b32 exec_lo, 0
	s_mov_b32 exec_hi, 0xf0000000
	global_store_dwordx4 v141, v[220:223], s[14:15] offset:256
	s_mov_b64 exec, -1
	v_cvt_pk_bf16_f32 v18, v18, v19
	v_cvt_pk_bf16_f32 v19, v20, v21
	v_cvt_pk_bf16_f32 v20, v10, v11
	v_cvt_pk_bf16_f32 v21, v12, v13
	ds_bpermute_b32 v232, v143, v18
	ds_bpermute_b32 v233, v143, v19
	ds_bpermute_b32 v234, v143, v20
	ds_bpermute_b32 v235, v143, v21
	s_waitcnt lgkmcnt(8)
	s_add_u32 s24, s4, 0x1b8000
	s_addc_u32 s25, s5, 0
	s_add_i32 s18, s26, 10
	s_mul_hi_u32 s15, s18, 0x2c00
	s_mul_i32 s14, s18, 0x2c00
	s_add_u32 s14, s6, s14
	s_addc_u32 s15, s7, s15
	global_store_dwordx4 v142, v[224:227], s[24:25]
	s_mov_b64 exec, 15
	global_store_dwordx4 v141, v[224:227], s[14:15]
	s_mov_b64 exec, -1
	v_cvt_pk_bf16_f32 v6, v6, v7
	v_cvt_pk_bf16_f32 v7, v8, v9
	v_cvt_pk_bf16_f32 v8, v2, v3
	v_cvt_pk_bf16_f32 v9, v4, v5
	ds_bpermute_b32 v236, v143, v6
	ds_bpermute_b32 v237, v143, v7
	ds_bpermute_b32 v238, v143, v8
	ds_bpermute_b32 v239, v143, v9
	s_waitcnt lgkmcnt(8)
	global_store_dwordx4 v142, v[228:231], s[24:25] offset:256
	s_mov_b64 exec, 15
	global_store_dwordx4 v141, v[228:231], s[14:15] offset:256
	s_mov_b64 exec, -1
	s_waitcnt lgkmcnt(4)
	s_add_u32 s24, s4, 0x1e4000
	s_addc_u32 s25, s5, 0
	s_add_i32 s18, s26, 11
	s_mul_hi_u32 s15, s18, 0x2c00
	s_mul_i32 s14, s18, 0x2c00
	s_add_u32 s14, s6, s14
	s_addc_u32 s15, s7, s15
	global_store_dwordx4 v142, v[232:235], s[24:25]
	s_mov_b32 exec_lo, 0
	s_mov_b32 exec_hi, 0xf0000000
	global_store_dwordx4 v141, v[232:235], s[14:15]
	s_mov_b64 exec, -1
	s_waitcnt lgkmcnt(0)
	global_store_dwordx4 v142, v[236:239], s[24:25] offset:256
	s_mov_b32 exec_lo, 0
	s_mov_b32 exec_hi, 0xf0000000
	global_store_dwordx4 v141, v[236:239], s[14:15] offset:256
	s_mov_b64 exec, -1
	s_andn2_b64 vcc, exec, s[44:45]
	s_mov_b64 s[14:15], -1
	s_cbranch_vccnz .LBB0_1022
	s_andn2_b64 vcc, exec, s[2:3]
	s_cbranch_vccnz .LBB0_1021
	s_barrier
	s_branch .LBB0_1021
